# FoX pair loop: one static s_setprio 1 for the long-pair waves (4-7), reset at exit
# baseline (speedup 1.0000x reference)
.Lfox_outer:
	s_lshr_b32 s23, s22, 6
	s_and_b32 s24, s22, 63
	s_sub_i32 s17, 0x43, s24
	s_bitcmp1_b32 s22, 2
	s_cselect_b32 s24, s17, s24
	s_cbranch_scc0 .Lfox_noprio
	s_setprio 1
.Lfox_noprio:
	s_lshl_b32 s15, s24, 1
	s_lshr_b32 s25, s23, 2
	s_and_b32 s26, s23, 3
	s_lshl_b32 s17, s23, 19
	s_add_u32 s4, s20, s17
	s_addc_u32 s5, s21, 0
	s_add_u32 s6, s4, 0x1c600000
	s_addc_u32 s7, s5, 0
	s_add_u32 s4, s4, 0x1b600000
	s_addc_u32 s5, s5, 0
	s_lshl_b32 s17, s23, 16
	s_add_u32 s8, s20, s17
	s_addc_u32 s9, s21, 0
	s_add_u32 s8, s8, 0x2880000
	s_addc_u32 s9, s9, 0
	s_lshl_b32 s17, s23, 14
	s_add_u32 s10, s20, s17
	s_addc_u32 s11, s21, 0
	s_add_u32 s10, s10, 0x1da00000
	s_addc_u32 s11, s11, 0
	s_lshl_b32 s17, s25, 23
	s_lshl_b32 s18, s26, 7
	s_add_i32 s17, s17, s18
	s_add_u32 s12, s20, s17
	s_addc_u32 s13, s21, 0
	s_add_u32 s12, s12, 0x14600000
	s_addc_u32 s13, s13, 0
	s_add_u32 s2, s20, 0x5600000
	s_addc_u32 s3, s21, 0
	s_lshl_b32 s27, s25, 12
	v_lshl_add_u32 v183, s15, 5, v195
	v_lshlrev_b32_e32 v205, 11, v183
	v_lshl_add_u32 v205, v196, 3, v205
	v_add_u32_e32 v206, 0x10000, v205
	v_lshlrev_b32_e32 v184, 2, v183
	global_load_dword v199, v184, s[10:11]
	global_load_dword v203, v184, s[10:11] offset:128
	v_add_u32_e32 v183, s27, v183
	v_mul_u32_u24_e32 v183, 0x1600, v183
	v_lshl_add_u32 v183, v196, 4, v183
	s_lshl_b32 s17, s26, 7
	v_add_u32_e32 v183, s17, v183
	v_add_u32_e32 v184, 0x2c000, v183
	global_load_dwordx4 v[38:41], v183, s[2:3]
	global_load_dwordx4 v[42:45], v183, s[2:3] offset:32
	global_load_dwordx4 v[46:49], v183, s[2:3] offset:64
	global_load_dwordx4 v[50:53], v183, s[2:3] offset:96
	global_load_dwordx4 v[54:57], v184, s[2:3]
	global_load_dwordx4 v[58:61], v184, s[2:3] offset:32
	global_load_dwordx4 v[62:65], v184, s[2:3] offset:64
	global_load_dwordx4 v[66:69], v184, s[2:3] offset:96
	s_mov_b32 s16, 0
	s_lshl_b32 s17, s16, 12
	v_add_u32_e32 v207, s17, v194
	global_load_dwordx4 v[2:5], v207, s[4:5]
	global_load_dwordx4 v[6:9], v207, s[4:5] offset:1024
	global_load_dwordx4 v[10:13], v207, s[4:5] offset:2048
	global_load_dwordx4 v[14:17], v207, s[4:5] offset:3072
	s_lshl_b32 s17, s16, 9
	v_add_u32_e32 v209, s17, v190
	s_mov_b64 exec, s[44:45]
	global_load_dwordx4 v[18:21], v209, s[8:9]
	s_mov_b64 exec, -1
	s_lshl_b32 s17, s16, 12
	v_add_u32_e32 v208, s17, v194
	global_load_dwordx4 v[22:25], v208, s[6:7]
	global_load_dwordx4 v[26:29], v208, s[6:7] offset:1024
	global_load_dwordx4 v[30:33], v208, s[6:7] offset:2048
	global_load_dwordx4 v[34:37], v208, s[6:7] offset:3072
	v_mov_b32_e32 v189, 0xf149f2ca
	v_mov_b32_e32 v197, 0xf149f2ca
	v_mov_b32_e32 v198, 0
	v_mov_b32_e32 v74, 0
	v_mov_b32_e32 v75, 0
	v_mov_b32_e32 v76, 0
	v_mov_b32_e32 v77, 0
	v_mov_b32_e32 v78, 0
	v_mov_b32_e32 v79, 0
	v_mov_b32_e32 v80, 0
	v_mov_b32_e32 v81, 0
	v_mov_b32_e32 v82, 0
	v_mov_b32_e32 v83, 0
	v_mov_b32_e32 v84, 0
	v_mov_b32_e32 v85, 0
	v_mov_b32_e32 v86, 0
	v_mov_b32_e32 v87, 0
	v_mov_b32_e32 v88, 0
	v_mov_b32_e32 v89, 0
	v_mov_b32_e32 v90, 0
	v_mov_b32_e32 v91, 0
	v_mov_b32_e32 v92, 0
	v_mov_b32_e32 v93, 0
	v_mov_b32_e32 v94, 0
	v_mov_b32_e32 v95, 0
	v_mov_b32_e32 v96, 0
	v_mov_b32_e32 v97, 0
	v_mov_b32_e32 v98, 0
	v_mov_b32_e32 v99, 0
	v_mov_b32_e32 v100, 0
	v_mov_b32_e32 v101, 0
	v_mov_b32_e32 v102, 0
	v_mov_b32_e32 v103, 0
	v_mov_b32_e32 v104, 0
	v_mov_b32_e32 v105, 0
	v_mov_b32_e32 v191, 0xf149f2ca
	v_mov_b32_e32 v201, 0xf149f2ca
	v_mov_b32_e32 v202, 0
	v_mov_b32_e32 v106, 0
	v_mov_b32_e32 v107, 0
	v_mov_b32_e32 v108, 0
	v_mov_b32_e32 v109, 0
	v_mov_b32_e32 v110, 0
	v_mov_b32_e32 v111, 0
	v_mov_b32_e32 v112, 0
	v_mov_b32_e32 v113, 0
	v_mov_b32_e32 v114, 0
	v_mov_b32_e32 v115, 0
	v_mov_b32_e32 v116, 0
	v_mov_b32_e32 v117, 0
	v_mov_b32_e32 v118, 0
	v_mov_b32_e32 v119, 0
	v_mov_b32_e32 v120, 0
	v_mov_b32_e32 v121, 0
	v_mov_b32_e32 v122, 0
	v_mov_b32_e32 v123, 0
	v_mov_b32_e32 v124, 0
	v_mov_b32_e32 v125, 0
	v_mov_b32_e32 v126, 0
	v_mov_b32_e32 v127, 0
	v_mov_b32_e32 v128, 0
	v_mov_b32_e32 v129, 0
	v_mov_b32_e32 v130, 0
	v_mov_b32_e32 v131, 0
	v_mov_b32_e32 v132, 0
	v_mov_b32_e32 v133, 0
	v_mov_b32_e32 v134, 0
	v_mov_b32_e32 v135, 0
	v_mov_b32_e32 v136, 0
	v_mov_b32_e32 v137, 0
	s_waitcnt vmcnt(9)
	v_mul_f32_e32 v199, 0x3fb8aa3b, v199
	v_mul_f32_e32 v203, 0x3fb8aa3b, v203
	s_cmp_eq_u32 s15, 0
	s_cbranch_scc1 .Lfox_tail

.Lfox_exit:
	s_setprio 0
	s_barrier
	s_branch .LBB0_715
